# P13 epilogue fused with the final RMSNorm: row sum-square partials exchanged between the 4 column-tile workgroups, x_final never written, P14 and its grid barrier removed; P3 pipelined epilogue + stag
# speedup vs baseline: 1.0121x; 1.0121x over previous
;     DEV void operator()(const f32x4 (&acc)[2][2][4][2], const Unit& u, int wr, int wc, int fr, int fq) const {
;     ...
;         for (int bj = 0; bj < 2; ++bj) {
;             f32x4 gv[2], gs[2];
; #pragma unroll
;             for (int n = 0; n < 2; ++n) { gv[n] = *(const f32x4*)(mod + (size_t)b * NMOD + gate_i * D + col0 + bj * 128 + NS * n) * coef;
;                 if (has_xn) gs[n] = *(const f32x4*)(g + col0 + bj * 128 + 4 * n) * (*(const f32x4*)(mod + (size_t)b * NMOD + scale_i * D + col0 + bj * 128 + 4 * n) + 1.f); }
; #pragma unroll
;             for (int ai = 0; ai < 2; ++ai)
; #pragma unroll
;                 for (int m = 0; m < 4; ++m) {
;                     const size_t p = (size_t)(row0 + ai * 128 + m * 16) * D + col0 + bj * 128;
;                     const f32x4 r0 = *(const f32x4*)(res + p), r1 = *(const f32x4*)(res + p + NS);
;                     const f32x4 o0 = r0 + gv[0] * acc[ai][bj][m][0], o1 = r1 + gv[1] * acc[ai][bj][m][1];
;                     *(f32x4*)(out + p) = o0; *(f32x4*)(out + p + NS) = o1;
;                     if (has_xn) { ss[ai * 4 + m] += (o0[0] * o0[0] + o0[1] * o0[1]) + (o0[2] * o0[2] + o0[3] * o0[3]) + (o1[0] * o1[0] + o1[1] * o1[1]) + (o1[2] * o1[2] + o1[3] * o1[3]);
.LBB0_1991:
	s_lshl_b32 s36, s67, 8
	s_add_u32 s36, s36, s48
	s_ashr_i32 s39, s67, 4
	s_mul_i32 s39, s39, 0x9000
	s_mov_b64 s[16:17], s[86:87]
	s_add_u32 s18, s94, s39
	s_addc_u32 s19, s95, 0
	s_add_u32 s18, s18, 0x8000
	s_addc_u32 s19, s19, 0
	s_lshl_b32 s37, s68, 8
	s_or_b32 s37, s37, s49
	v_lshl_add_u32 v166, v156, 2, s37
	v_add_u32_e32 v167, s36, v147
	v_lshlrev_b32_e32 v252, 2, v166
	v_lshl_add_u32 v243, v167, 12, v252
	v_lshlrev_b32_e32 v253, 6, v167
	v_mov_b32_e32 v248, 0
	v_mov_b32_e32 v249, 0
	v_mov_b32_e32 v250, 0
	v_mov_b32_e32 v251, 0
	v_mov_b32_e32 v244, 0
	v_mov_b32_e32 v245, 0
	v_mov_b32_e32 v246, 0
	v_mov_b32_e32 v247, 0
	global_load_dwordx4 v[142:145], v252, s[18:19] offset:0
	global_load_dwordx4 v[148:151], v252, s[18:19] offset:64
	global_load_dwordx4 v[152:155], v252, s[18:19] offset:512
	global_load_dwordx4 v[162:165], v252, s[18:19] offset:576
	global_load_dwordx4 v[166:169], v243, s[16:17] offset:0
	global_load_dwordx4 v[170:173], v243, s[16:17] offset:64
	global_load_dwordx4 v[174:177], v243, s[16:17] offset:512
	global_load_dwordx4 v[178:181], v243, s[16:17] offset:576
	s_add_u32 s20, s16, 0x10000
	s_addc_u32 s21, s17, 0
	global_load_dwordx4 v[182:185], v243, s[20:21] offset:0
	global_load_dwordx4 v[186:189], v243, s[20:21] offset:64
	global_load_dwordx4 v[190:193], v243, s[20:21] offset:512
	global_load_dwordx4 v[194:197], v243, s[20:21] offset:576
	s_add_u32 s20, s16, 0x20000
	s_addc_u32 s21, s17, 0
	global_load_dwordx4 v[198:201], v243, s[20:21] offset:0
	global_load_dwordx4 v[202:205], v243, s[20:21] offset:64
	global_load_dwordx4 v[206:209], v243, s[20:21] offset:512
	global_load_dwordx4 v[210:213], v243, s[20:21] offset:576
	s_waitcnt vmcnt(12)
	v_pk_mul_f32 v[142:143], v[142:143], 0.5 op_sel_hi:[1,0]
	v_pk_mul_f32 v[144:145], v[144:145], 0.5 op_sel_hi:[1,0]
	v_pk_mul_f32 v[148:149], v[148:149], 0.5 op_sel_hi:[1,0]
	v_pk_mul_f32 v[150:151], v[150:151], 0.5 op_sel_hi:[1,0]
	v_pk_mul_f32 v[152:153], v[152:153], 0.5 op_sel_hi:[1,0]
	v_pk_mul_f32 v[154:155], v[154:155], 0.5 op_sel_hi:[1,0]
	v_pk_mul_f32 v[162:163], v[162:163], 0.5 op_sel_hi:[1,0]
	v_pk_mul_f32 v[164:165], v[164:165], 0.5 op_sel_hi:[1,0]
	s_waitcnt vmcnt(8)
	v_pk_fma_f32 v[126:127], v[126:127], v[142:143], v[166:167]
	v_pk_fma_f32 v[128:129], v[128:129], v[144:145], v[168:169]
	v_pk_fma_f32 v[122:123], v[122:123], v[148:149], v[170:171]
	v_pk_fma_f32 v[124:125], v[124:125], v[150:151], v[172:173]
	v_pk_fma_f32 v[70:71], v[70:71], v[152:153], v[174:175]
	v_pk_fma_f32 v[72:73], v[72:73], v[154:155], v[176:177]
	v_pk_fma_f32 v[66:67], v[66:67], v[162:163], v[178:179]
	v_pk_fma_f32 v[68:69], v[68:69], v[164:165], v[180:181]
	s_add_u32 s20, s16, 0x30000
	s_addc_u32 s21, s17, 0
	global_load_dwordx4 v[166:169], v243, s[20:21] offset:0
	global_load_dwordx4 v[170:173], v243, s[20:21] offset:64
	global_load_dwordx4 v[174:177], v243, s[20:21] offset:512
	global_load_dwordx4 v[178:181], v243, s[20:21] offset:576
	v_fmac_f32_e32 v248, v126, v126
	v_fmac_f32_e32 v248, v127, v127
	v_fmac_f32_e32 v248, v128, v128
	v_fmac_f32_e32 v248, v129, v129
	v_fmac_f32_e32 v248, v122, v122
	v_fmac_f32_e32 v248, v123, v123
	v_fmac_f32_e32 v248, v124, v124
	v_fmac_f32_e32 v248, v125, v125
	v_fmac_f32_e32 v248, v70, v70
	v_fmac_f32_e32 v248, v71, v71
	v_fmac_f32_e32 v248, v72, v72
	v_fmac_f32_e32 v248, v73, v73
	v_fmac_f32_e32 v248, v66, v66
	v_fmac_f32_e32 v248, v67, v67
	v_fmac_f32_e32 v248, v68, v68
	v_fmac_f32_e32 v248, v69, v69
	s_waitcnt vmcnt(8)
	v_pk_fma_f32 v[118:119], v[118:119], v[142:143], v[182:183]
	v_pk_fma_f32 v[120:121], v[120:121], v[144:145], v[184:185]
	v_pk_fma_f32 v[114:115], v[114:115], v[148:149], v[186:187]
	v_pk_fma_f32 v[116:117], v[116:117], v[150:151], v[188:189]
	v_pk_fma_f32 v[54:55], v[54:55], v[152:153], v[190:191]
	v_pk_fma_f32 v[56:57], v[56:57], v[154:155], v[192:193]
	v_pk_fma_f32 v[50:51], v[50:51], v[162:163], v[194:195]
	v_pk_fma_f32 v[52:53], v[52:53], v[164:165], v[196:197]
	s_add_u32 s20, s16, 0x80000
	s_addc_u32 s21, s17, 0
	global_load_dwordx4 v[182:185], v243, s[20:21] offset:0
	global_load_dwordx4 v[186:189], v243, s[20:21] offset:64
	global_load_dwordx4 v[190:193], v243, s[20:21] offset:512
	global_load_dwordx4 v[194:197], v243, s[20:21] offset:576
	v_fmac_f32_e32 v249, v118, v118
	v_fmac_f32_e32 v249, v119, v119
	v_fmac_f32_e32 v249, v120, v120
	v_fmac_f32_e32 v249, v121, v121
	v_fmac_f32_e32 v249, v114, v114
	v_fmac_f32_e32 v249, v115, v115
	v_fmac_f32_e32 v249, v116, v116
	v_fmac_f32_e32 v249, v117, v117
	v_fmac_f32_e32 v249, v54, v54
	v_fmac_f32_e32 v249, v55, v55
	v_fmac_f32_e32 v249, v56, v56
	v_fmac_f32_e32 v249, v57, v57
	v_fmac_f32_e32 v249, v50, v50
	v_fmac_f32_e32 v249, v51, v51
	v_fmac_f32_e32 v249, v52, v52
	v_fmac_f32_e32 v249, v53, v53
	s_waitcnt vmcnt(8)
	v_pk_fma_f32 v[110:111], v[110:111], v[142:143], v[198:199]
	v_pk_fma_f32 v[112:113], v[112:113], v[144:145], v[200:201]
	v_pk_fma_f32 v[106:107], v[106:107], v[148:149], v[202:203]
	v_pk_fma_f32 v[108:109], v[108:109], v[150:151], v[204:205]
	v_pk_fma_f32 v[46:47], v[46:47], v[152:153], v[206:207]
	v_pk_fma_f32 v[48:49], v[48:49], v[154:155], v[208:209]
	v_pk_fma_f32 v[42:43], v[42:43], v[162:163], v[210:211]
	v_pk_fma_f32 v[44:45], v[44:45], v[164:165], v[212:213]
	s_add_u32 s20, s16, 0x90000
	s_addc_u32 s21, s17, 0
	global_load_dwordx4 v[198:201], v243, s[20:21] offset:0
	global_load_dwordx4 v[202:205], v243, s[20:21] offset:64
	global_load_dwordx4 v[206:209], v243, s[20:21] offset:512
	global_load_dwordx4 v[210:213], v243, s[20:21] offset:576
	v_fmac_f32_e32 v250, v110, v110
	v_fmac_f32_e32 v250, v111, v111
	v_fmac_f32_e32 v250, v112, v112
	v_fmac_f32_e32 v250, v113, v113
	v_fmac_f32_e32 v250, v106, v106
	v_fmac_f32_e32 v250, v107, v107
	v_fmac_f32_e32 v250, v108, v108
	v_fmac_f32_e32 v250, v109, v109
	v_fmac_f32_e32 v250, v46, v46
	v_fmac_f32_e32 v250, v47, v47
	v_fmac_f32_e32 v250, v48, v48
	v_fmac_f32_e32 v250, v49, v49
	v_fmac_f32_e32 v250, v42, v42
	v_fmac_f32_e32 v250, v43, v43
	v_fmac_f32_e32 v250, v44, v44
	v_fmac_f32_e32 v250, v45, v45
	s_waitcnt vmcnt(8)
; DEV u32x4 pack8v(const f32x4 a, const f32x4 b) { u32x4 w; w.x = cvt_pk_bf16(a[0], a[1]); w.y = cvt_pk_bf16(a[2], a[3]); w.z = cvt_pk_bf16(b[0], b[1]); w.w = cvt_pk_bf16(b[2], b[3]); return w; }
;     DEV void operator()(const f32x4 (&acc)[2][2][4][2], const Unit& u, int wr, int wc, int fr, int fq) const {
;     ...
;             for (int ai = 0; ai < 2; ++ai)
; #pragma unroll
;                 for (int m = 0; m < 4; ++m) {
;                     const size_t p = (size_t)(row0 + ai * 128 + m * 16) * D + col0 + bj * 128;
;                     const f32x4 r0 = *(const f32x4*)(res + p), r1 = *(const f32x4*)(res + p + NS);
;                     const f32x4 o0 = r0 + gv[0] * acc[ai][bj][m][0], o1 = r1 + gv[1] * acc[ai][bj][m][1];
;                     *(f32x4*)(out + p) = o0; *(f32x4*)(out + p + NS) = o1;
;                     if (has_xn) { ss[ai * 4 + m] += (o0[0] * o0[0] + o0[1] * o0[1]) + (o0[2] * o0[2] + o0[3] * o0[3]) + (o1[0] * o1[0] + o1[1] * o1[1]) + (o1[2] * o1[2] + o1[3] * o1[3]);
;                         *(u32x4*)(xn + (size_t)(grow0 + ai * 128 + m * 16) * D + col0 + bj * 128) = pack8v(o0 * gs[0], o1 * gs[1]); }
;                 }
;         }
;         if (has_xn) {
; #pragma unroll
;             for (int i = 0; i < 8; ++i) { float v = ss[i]; v += __shfl_xor(v, 16); v += __shfl_xor(v, 32); if (fq == 0) rs[(size_t)(grow0 + (i >> 2) * 128 + (i & 3) * 16) * 16 + u.pn * 4 + wc] = v; }
	v_pk_fma_f32 v[102:103], v[102:103], v[142:143], v[166:167]
	v_pk_fma_f32 v[104:105], v[104:105], v[144:145], v[168:169]
	v_pk_fma_f32 v[98:99], v[98:99], v[148:149], v[170:171]
	v_pk_fma_f32 v[100:101], v[100:101], v[150:151], v[172:173]
	v_pk_fma_f32 v[38:39], v[38:39], v[152:153], v[174:175]
	v_pk_fma_f32 v[40:41], v[40:41], v[154:155], v[176:177]
	v_pk_fma_f32 v[34:35], v[34:35], v[162:163], v[178:179]
	v_pk_fma_f32 v[36:37], v[36:37], v[164:165], v[180:181]
	s_add_u32 s20, s16, 0xa0000
	s_addc_u32 s21, s17, 0
	global_load_dwordx4 v[166:169], v243, s[20:21] offset:0
	global_load_dwordx4 v[170:173], v243, s[20:21] offset:64
	global_load_dwordx4 v[174:177], v243, s[20:21] offset:512
	global_load_dwordx4 v[178:181], v243, s[20:21] offset:576
	v_fmac_f32_e32 v251, v102, v102
	v_fmac_f32_e32 v251, v103, v103
	v_fmac_f32_e32 v251, v104, v104
	v_fmac_f32_e32 v251, v105, v105
	v_fmac_f32_e32 v251, v98, v98
	v_fmac_f32_e32 v251, v99, v99
	v_fmac_f32_e32 v251, v100, v100
	v_fmac_f32_e32 v251, v101, v101
	v_fmac_f32_e32 v251, v38, v38
	v_fmac_f32_e32 v251, v39, v39
	v_fmac_f32_e32 v251, v40, v40
	v_fmac_f32_e32 v251, v41, v41
	v_fmac_f32_e32 v251, v34, v34
	v_fmac_f32_e32 v251, v35, v35
	v_fmac_f32_e32 v251, v36, v36
	v_fmac_f32_e32 v251, v37, v37
	s_waitcnt vmcnt(8)
	v_pk_fma_f32 v[94:95], v[94:95], v[142:143], v[182:183]
	v_pk_fma_f32 v[96:97], v[96:97], v[144:145], v[184:185]
	v_pk_fma_f32 v[90:91], v[90:91], v[148:149], v[186:187]
	v_pk_fma_f32 v[92:93], v[92:93], v[150:151], v[188:189]
	v_pk_fma_f32 v[30:31], v[30:31], v[152:153], v[190:191]
	v_pk_fma_f32 v[32:33], v[32:33], v[154:155], v[192:193]
	v_pk_fma_f32 v[26:27], v[26:27], v[162:163], v[194:195]
	v_pk_fma_f32 v[28:29], v[28:29], v[164:165], v[196:197]
	s_add_u32 s20, s16, 0xb0000
	s_addc_u32 s21, s17, 0
	global_load_dwordx4 v[182:185], v243, s[20:21] offset:0
	global_load_dwordx4 v[186:189], v243, s[20:21] offset:64
	global_load_dwordx4 v[190:193], v243, s[20:21] offset:512
	global_load_dwordx4 v[194:197], v243, s[20:21] offset:576
	v_fmac_f32_e32 v244, v94, v94
	v_fmac_f32_e32 v244, v95, v95
	v_fmac_f32_e32 v244, v96, v96
	v_fmac_f32_e32 v244, v97, v97
	v_fmac_f32_e32 v244, v90, v90
	v_fmac_f32_e32 v244, v91, v91
	v_fmac_f32_e32 v244, v92, v92
	v_fmac_f32_e32 v244, v93, v93
	v_fmac_f32_e32 v244, v30, v30
	v_fmac_f32_e32 v244, v31, v31
	v_fmac_f32_e32 v244, v32, v32
	v_fmac_f32_e32 v244, v33, v33
	v_fmac_f32_e32 v244, v26, v26
	v_fmac_f32_e32 v244, v27, v27
	v_fmac_f32_e32 v244, v28, v28
	v_fmac_f32_e32 v244, v29, v29
	s_waitcnt vmcnt(8)
	v_pk_fma_f32 v[86:87], v[86:87], v[142:143], v[198:199]
	v_pk_fma_f32 v[88:89], v[88:89], v[144:145], v[200:201]
	v_pk_fma_f32 v[82:83], v[82:83], v[148:149], v[202:203]
	v_pk_fma_f32 v[84:85], v[84:85], v[150:151], v[204:205]
	v_pk_fma_f32 v[22:23], v[22:23], v[152:153], v[206:207]
	v_pk_fma_f32 v[24:25], v[24:25], v[154:155], v[208:209]
	v_pk_fma_f32 v[18:19], v[18:19], v[162:163], v[210:211]
	v_pk_fma_f32 v[20:21], v[20:21], v[164:165], v[212:213]
	v_fmac_f32_e32 v245, v86, v86
	v_fmac_f32_e32 v245, v87, v87
	v_fmac_f32_e32 v245, v88, v88
	v_fmac_f32_e32 v245, v89, v89
	v_fmac_f32_e32 v245, v82, v82
	v_fmac_f32_e32 v245, v83, v83
	v_fmac_f32_e32 v245, v84, v84
	v_fmac_f32_e32 v245, v85, v85
	v_fmac_f32_e32 v245, v22, v22
	v_fmac_f32_e32 v245, v23, v23
	v_fmac_f32_e32 v245, v24, v24
	v_fmac_f32_e32 v245, v25, v25
	v_fmac_f32_e32 v245, v18, v18
	v_fmac_f32_e32 v245, v19, v19
	v_fmac_f32_e32 v245, v20, v20
	v_fmac_f32_e32 v245, v21, v21
	s_waitcnt vmcnt(4)
	v_pk_fma_f32 v[78:79], v[78:79], v[142:143], v[166:167]
	v_pk_fma_f32 v[80:81], v[80:81], v[144:145], v[168:169]
	v_pk_fma_f32 v[74:75], v[74:75], v[148:149], v[170:171]
	v_pk_fma_f32 v[76:77], v[76:77], v[150:151], v[172:173]
	v_pk_fma_f32 v[14:15], v[14:15], v[152:153], v[174:175]
	v_pk_fma_f32 v[16:17], v[16:17], v[154:155], v[176:177]
	v_pk_fma_f32 v[10:11], v[10:11], v[162:163], v[178:179]
	v_pk_fma_f32 v[12:13], v[12:13], v[164:165], v[180:181]
	v_fmac_f32_e32 v246, v78, v78
	v_fmac_f32_e32 v246, v79, v79
	v_fmac_f32_e32 v246, v80, v80
	v_fmac_f32_e32 v246, v81, v81
	v_fmac_f32_e32 v246, v74, v74
	v_fmac_f32_e32 v246, v75, v75
	v_fmac_f32_e32 v246, v76, v76
	v_fmac_f32_e32 v246, v77, v77
	v_fmac_f32_e32 v246, v14, v14
	v_fmac_f32_e32 v246, v15, v15
	v_fmac_f32_e32 v246, v16, v16
	v_fmac_f32_e32 v246, v17, v17
	v_fmac_f32_e32 v246, v10, v10
	v_fmac_f32_e32 v246, v11, v11
	v_fmac_f32_e32 v246, v12, v12
	v_fmac_f32_e32 v246, v13, v13
	s_waitcnt vmcnt(0)
	v_pk_fma_f32 v[62:63], v[62:63], v[142:143], v[182:183]
	v_pk_fma_f32 v[64:65], v[64:65], v[144:145], v[184:185]
	v_pk_fma_f32 v[58:59], v[58:59], v[148:149], v[186:187]
	v_pk_fma_f32 v[60:61], v[60:61], v[150:151], v[188:189]
	v_pk_fma_f32 v[6:7], v[6:7], v[152:153], v[190:191]
	v_pk_fma_f32 v[8:9], v[8:9], v[154:155], v[192:193]
	v_pk_fma_f32 v[2:3], v[2:3], v[162:163], v[194:195]
	v_pk_fma_f32 v[4:5], v[4:5], v[164:165], v[196:197]
	v_fmac_f32_e32 v247, v62, v62
	v_fmac_f32_e32 v247, v63, v63
	v_fmac_f32_e32 v247, v64, v64
	v_fmac_f32_e32 v247, v65, v65
	v_fmac_f32_e32 v247, v58, v58
	v_fmac_f32_e32 v247, v59, v59
	v_fmac_f32_e32 v247, v60, v60
	v_fmac_f32_e32 v247, v61, v61
	v_fmac_f32_e32 v247, v6, v6
	v_fmac_f32_e32 v247, v7, v7
	v_fmac_f32_e32 v247, v8, v8
	v_fmac_f32_e32 v247, v9, v9
	v_fmac_f32_e32 v247, v2, v2
	v_fmac_f32_e32 v247, v3, v3
	v_fmac_f32_e32 v247, v4, v4
	v_fmac_f32_e32 v247, v5, v5
	v_mbcnt_lo_u32_b32 v255, -1, 0
	v_mbcnt_hi_u32_b32 v255, -1, v255
	v_xor_b32_e32 v254, 16, v255
	v_xor_b32_e32 v255, 32, v255
	v_lshlrev_b32_e32 v254, 2, v254
	v_lshlrev_b32_e32 v255, 2, v255
	ds_bpermute_b32 v182, v254, v248
	ds_bpermute_b32 v183, v254, v249
	ds_bpermute_b32 v184, v254, v250
	ds_bpermute_b32 v185, v254, v251
	ds_bpermute_b32 v186, v254, v244
	ds_bpermute_b32 v187, v254, v245
	ds_bpermute_b32 v188, v254, v246
	ds_bpermute_b32 v189, v254, v247
	s_waitcnt lgkmcnt(0)
;     DEV void operator()(const f32x4 (&acc)[2][2][4][2], const Unit& u, int wr, int wc, int fr, int fq) const {
;     ...
;         if (has_xn) {
; #pragma unroll
;             for (int i = 0; i < 8; ++i) { float v = ss[i]; v += __shfl_xor(v, 16); v += __shfl_xor(v, 32); if (fq == 0) rs[(size_t)(grow0 + (i >> 2) * 128 + (i & 3) * 16) * 16 + u.pn * 4 + wc] = v; }
;         }
; DEV void final_norm_phase(float* xo, const float* g, int gw, int NGW, int lane) {
;     ...
;         for (int r = 0; r < 2; ++r) {
;             float s = 0.f;
; #pragma unroll
;             for (int j = 0; j < 4; ++j) s += (v[r][j].x * v[r][j].x + v[r][j].y * v[r][j].y) + (v[r][j].z * v[r][j].z + v[r][j].w * v[r][j].w);
;             const float rstd = rsqrtf(wave_sum(s) * (1.f / D) + EPS);
	v_add_f32_e32 v248, v248, v182
	v_add_f32_e32 v249, v249, v183
	v_add_f32_e32 v250, v250, v184
	v_add_f32_e32 v251, v251, v185
	v_add_f32_e32 v244, v244, v186
	v_add_f32_e32 v245, v245, v187
	v_add_f32_e32 v246, v246, v188
	v_add_f32_e32 v247, v247, v189
	ds_bpermute_b32 v182, v255, v248
	ds_bpermute_b32 v183, v255, v249
	ds_bpermute_b32 v184, v255, v250
	ds_bpermute_b32 v185, v255, v251
	ds_bpermute_b32 v186, v255, v244
	ds_bpermute_b32 v187, v255, v245
	ds_bpermute_b32 v188, v255, v246
	ds_bpermute_b32 v189, v255, v247
	s_waitcnt lgkmcnt(0)
	v_add_f32_e32 v248, v248, v182
	v_add_f32_e32 v249, v249, v183
	v_add_f32_e32 v250, v250, v184
	v_add_f32_e32 v251, v251, v185
	v_add_f32_e32 v244, v244, v186
	v_add_f32_e32 v245, v245, v187
	v_add_f32_e32 v246, v246, v188
	v_add_f32_e32 v247, v247, v189
	s_lshr_b32 s37, s49, 3
	s_lshl_b32 s38, s68, 4
	s_add_u32 s37, s37, s38
	s_add_u32 s24, s88, 0x3ce00000
	s_addc_u32 s25, s89, 0
	s_add_u32 s20, s24, s37
	s_addc_u32 s21, s25, 0
	v_cmp_eq_u32_e32 vcc, 0, v156
	s_nop 4
	s_and_saveexec_b64 s[28:29], vcc
	global_store_dword v253, v248, s[20:21] offset:0 sc0 sc1
	global_store_dword v253, v249, s[20:21] offset:1024 sc0 sc1
	global_store_dword v253, v250, s[20:21] offset:2048 sc0 sc1
	global_store_dword v253, v251, s[20:21] offset:3072 sc0 sc1
	s_add_u32 s20, s20, 0x2000
	s_addc_u32 s21, s21, 0
	global_store_dword v253, v244, s[20:21] offset:0 sc0 sc1
	global_store_dword v253, v245, s[20:21] offset:1024 sc0 sc1
	global_store_dword v253, v246, s[20:21] offset:2048 sc0 sc1
	global_store_dword v253, v247, s[20:21] offset:3072 sc0 sc1
	s_or_b64 exec, exec, s[28:29]
	s_waitcnt vmcnt(0)
	s_barrier
	s_or_b32 s37, s48, s49
	s_cmp_eq_u32 s37, 0
	s_cbranch_scc0 .Lp13f_nopoll
	s_lshl_b32 s37, s67, 6
	s_add_u32 s37, s37, 0x4000
	s_add_u32 s26, s88, s37
	s_addc_u32 s27, s89, 0
	v_mov_b32_e32 v182, 0
	v_mov_b32_e32 v183, 1
	s_mov_b64 s[28:29], exec
	s_mov_b64 exec, 1
	global_atomic_add v182, v183, s[26:27] offset:0
	s_mov_b32 s38, 0
.Lp13f_poll:
	global_load_dword v184, v182, s[26:27] offset:0 sc1
	s_waitcnt vmcnt(0)
	v_readfirstlane_b32 s37, v184
	s_cmp_ge_u32 s37, 4
	s_cbranch_scc1 .Lp13f_polled
	s_sleep 2
	s_add_u32 s38, s38, 1
	s_cmp_lt_u32 s38, 0x80000
	s_cbranch_scc1 .Lp13f_poll
.Lp13f_polled:
	buffer_inv sc1
	s_waitcnt vmcnt(0)
	s_mov_b64 exec, s[28:29]
.Lp13f_nopoll:
	s_barrier
	v_lshl_add_u32 v253, v156, 4, v253
	global_load_dwordx4 v[166:169], v253, s[24:25] offset:0 sc1
	global_load_dwordx4 v[170:173], v253, s[24:25] offset:1024 sc1
	global_load_dwordx4 v[174:177], v253, s[24:25] offset:2048 sc1
	global_load_dwordx4 v[178:181], v253, s[24:25] offset:3072 sc1
	s_add_u32 s24, s24, 0x2000
	s_addc_u32 s25, s25, 0
	global_load_dwordx4 v[198:201], v253, s[24:25] offset:0 sc1
	global_load_dwordx4 v[202:205], v253, s[24:25] offset:1024 sc1
	global_load_dwordx4 v[206:209], v253, s[24:25] offset:2048 sc1
	global_load_dwordx4 v[210:213], v253, s[24:25] offset:3072 sc1
	global_load_dwordx4 v[142:145], v252, s[84:85] offset:0
	global_load_dwordx4 v[148:151], v252, s[84:85] offset:64
	global_load_dwordx4 v[152:155], v252, s[84:85] offset:512
	global_load_dwordx4 v[162:165], v252, s[84:85] offset:576
	s_waitcnt vmcnt(0)
	v_add_f32_e32 v166, v166, v167
	v_add_f32_e32 v168, v168, v169
	v_add_f32_e32 v248, v166, v168
	v_add_f32_e32 v170, v170, v171
	v_add_f32_e32 v172, v172, v173
	v_add_f32_e32 v249, v170, v172
	v_add_f32_e32 v174, v174, v175
	v_add_f32_e32 v176, v176, v177
	v_add_f32_e32 v250, v174, v176
	v_add_f32_e32 v178, v178, v179
	v_add_f32_e32 v180, v180, v181
	v_add_f32_e32 v251, v178, v180
	v_add_f32_e32 v198, v198, v199
	v_add_f32_e32 v200, v200, v201
	v_add_f32_e32 v244, v198, v200
	v_add_f32_e32 v202, v202, v203
	v_add_f32_e32 v204, v204, v205
	v_add_f32_e32 v245, v202, v204
	v_add_f32_e32 v206, v206, v207
	v_add_f32_e32 v208, v208, v209
	v_add_f32_e32 v246, v206, v208
	v_add_f32_e32 v210, v210, v211
	v_add_f32_e32 v212, v212, v213
	v_add_f32_e32 v247, v210, v212
	ds_bpermute_b32 v182, v254, v248
	ds_bpermute_b32 v183, v254, v249
	ds_bpermute_b32 v184, v254, v250
	ds_bpermute_b32 v185, v254, v251
	ds_bpermute_b32 v186, v254, v244
	ds_bpermute_b32 v187, v254, v245
	ds_bpermute_b32 v188, v254, v246
	ds_bpermute_b32 v189, v254, v247
	s_waitcnt lgkmcnt(0)
	v_add_f32_e32 v248, v248, v182
	v_add_f32_e32 v249, v249, v183
	v_add_f32_e32 v250, v250, v184
	v_add_f32_e32 v251, v251, v185
	v_add_f32_e32 v244, v244, v186
	v_add_f32_e32 v245, v245, v187
	v_add_f32_e32 v246, v246, v188
	v_add_f32_e32 v247, v247, v189
	ds_bpermute_b32 v182, v255, v248
	ds_bpermute_b32 v183, v255, v249
	ds_bpermute_b32 v184, v255, v250
	ds_bpermute_b32 v185, v255, v251
	ds_bpermute_b32 v186, v255, v244
	ds_bpermute_b32 v187, v255, v245
	ds_bpermute_b32 v188, v255, v246
	ds_bpermute_b32 v189, v255, v247
	s_waitcnt lgkmcnt(0)
; DEV void final_norm_phase(float* xo, const float* g, int gw, int NGW, int lane) {
;     ...
;         for (int r = 0; r < 2; ++r) {
;             float s = 0.f;
; #pragma unroll
;             for (int j = 0; j < 4; ++j) s += (v[r][j].x * v[r][j].x + v[r][j].y * v[r][j].y) + (v[r][j].z * v[r][j].z + v[r][j].w * v[r][j].w);
;             const float rstd = rsqrtf(wave_sum(s) * (1.f / D) + EPS);
; #pragma unroll
;             for (int j = 0; j < 4; ++j) __builtin_nontemporal_store((v[r][j] * rstd) * gm[j], &xr[r * 256 + 64 * j]);
;         }
	v_add_f32_e32 v248, v248, v182
	v_add_f32_e32 v249, v249, v183
	v_add_f32_e32 v250, v250, v184
	v_add_f32_e32 v251, v251, v185
	v_add_f32_e32 v244, v244, v186
	v_add_f32_e32 v245, v245, v187
	v_add_f32_e32 v246, v246, v188
	v_add_f32_e32 v247, v247, v189
	v_mov_b32_e32 v182, 0x358637bd
	s_mov_b32 s37, 0x3a800000
	v_fma_f32 v248, v248, s37, v182
	v_fma_f32 v249, v249, s37, v182
	v_fma_f32 v250, v250, s37, v182
	v_fma_f32 v251, v251, s37, v182
	v_fma_f32 v244, v244, s37, v182
	v_fma_f32 v245, v245, s37, v182
	v_fma_f32 v246, v246, s37, v182
	v_fma_f32 v247, v247, s37, v182
	v_rsq_f32_e32 v248, v248
	v_rsq_f32_e32 v249, v249
	v_rsq_f32_e32 v250, v250
	v_rsq_f32_e32 v251, v251
	v_rsq_f32_e32 v244, v244
	v_rsq_f32_e32 v245, v245
	v_rsq_f32_e32 v246, v246
	v_rsq_f32_e32 v247, v247
	s_nop 1
	v_mul_f32_e32 v126, v126, v248
	v_mul_f32_e32 v127, v127, v248
	v_mul_f32_e32 v128, v128, v248
	v_mul_f32_e32 v129, v129, v248
	v_pk_mul_f32 v[126:127], v[126:127], v[142:143]
	v_pk_mul_f32 v[128:129], v[128:129], v[144:145]
	v_mul_f32_e32 v122, v122, v248
	v_mul_f32_e32 v123, v123, v248
	v_mul_f32_e32 v124, v124, v248
	v_mul_f32_e32 v125, v125, v248
	v_pk_mul_f32 v[122:123], v[122:123], v[148:149]
	v_pk_mul_f32 v[124:125], v[124:125], v[150:151]
	v_mul_f32_e32 v70, v70, v248
	v_mul_f32_e32 v71, v71, v248
	v_mul_f32_e32 v72, v72, v248
	v_mul_f32_e32 v73, v73, v248
	v_pk_mul_f32 v[70:71], v[70:71], v[152:153]
	v_pk_mul_f32 v[72:73], v[72:73], v[154:155]
	v_mul_f32_e32 v66, v66, v248
	v_mul_f32_e32 v67, v67, v248
	v_mul_f32_e32 v68, v68, v248
	v_mul_f32_e32 v69, v69, v248
	v_pk_mul_f32 v[66:67], v[66:67], v[162:163]
	v_pk_mul_f32 v[68:69], v[68:69], v[164:165]
	global_store_dwordx4 v243, v[126:129], s[16:17] offset:0 nt
	global_store_dwordx4 v243, v[122:125], s[16:17] offset:64 nt
	global_store_dwordx4 v243, v[70:73], s[16:17] offset:512 nt
	global_store_dwordx4 v243, v[66:69], s[16:17] offset:576 nt
	s_add_u32 s20, s16, 0x10000
	s_addc_u32 s21, s17, 0
	v_mul_f32_e32 v118, v118, v249
	v_mul_f32_e32 v119, v119, v249
	v_mul_f32_e32 v120, v120, v249
	v_mul_f32_e32 v121, v121, v249
	v_pk_mul_f32 v[118:119], v[118:119], v[142:143]
	v_pk_mul_f32 v[120:121], v[120:121], v[144:145]
	v_mul_f32_e32 v114, v114, v249
	v_mul_f32_e32 v115, v115, v249
	v_mul_f32_e32 v116, v116, v249
	v_mul_f32_e32 v117, v117, v249
	v_pk_mul_f32 v[114:115], v[114:115], v[148:149]
	v_pk_mul_f32 v[116:117], v[116:117], v[150:151]
	v_mul_f32_e32 v54, v54, v249
	v_mul_f32_e32 v55, v55, v249
	v_mul_f32_e32 v56, v56, v249
	v_mul_f32_e32 v57, v57, v249
	v_pk_mul_f32 v[54:55], v[54:55], v[152:153]
	v_pk_mul_f32 v[56:57], v[56:57], v[154:155]
	v_mul_f32_e32 v50, v50, v249
	v_mul_f32_e32 v51, v51, v249
	v_mul_f32_e32 v52, v52, v249
	v_mul_f32_e32 v53, v53, v249
	v_pk_mul_f32 v[50:51], v[50:51], v[162:163]
	v_pk_mul_f32 v[52:53], v[52:53], v[164:165]
	global_store_dwordx4 v243, v[118:121], s[20:21] offset:0 nt
	global_store_dwordx4 v243, v[114:117], s[20:21] offset:64 nt
	global_store_dwordx4 v243, v[54:57], s[20:21] offset:512 nt
	global_store_dwordx4 v243, v[50:53], s[20:21] offset:576 nt
	s_add_u32 s20, s16, 0x20000
	s_addc_u32 s21, s17, 0
	v_mul_f32_e32 v110, v110, v250
	v_mul_f32_e32 v111, v111, v250
	v_mul_f32_e32 v112, v112, v250
	v_mul_f32_e32 v113, v113, v250
	v_pk_mul_f32 v[110:111], v[110:111], v[142:143]
	v_pk_mul_f32 v[112:113], v[112:113], v[144:145]
	v_mul_f32_e32 v106, v106, v250
	v_mul_f32_e32 v107, v107, v250
	v_mul_f32_e32 v108, v108, v250
	v_mul_f32_e32 v109, v109, v250
	v_pk_mul_f32 v[106:107], v[106:107], v[148:149]
	v_pk_mul_f32 v[108:109], v[108:109], v[150:151]
	v_mul_f32_e32 v46, v46, v250
	v_mul_f32_e32 v47, v47, v250
	v_mul_f32_e32 v48, v48, v250
	v_mul_f32_e32 v49, v49, v250
	v_pk_mul_f32 v[46:47], v[46:47], v[152:153]
	v_pk_mul_f32 v[48:49], v[48:49], v[154:155]
	v_mul_f32_e32 v42, v42, v250
	v_mul_f32_e32 v43, v43, v250
	v_mul_f32_e32 v44, v44, v250
	v_mul_f32_e32 v45, v45, v250
	v_pk_mul_f32 v[42:43], v[42:43], v[162:163]
	v_pk_mul_f32 v[44:45], v[44:45], v[164:165]
	global_store_dwordx4 v243, v[110:113], s[20:21] offset:0 nt
	global_store_dwordx4 v243, v[106:109], s[20:21] offset:64 nt
	global_store_dwordx4 v243, v[46:49], s[20:21] offset:512 nt
	global_store_dwordx4 v243, v[42:45], s[20:21] offset:576 nt
	s_add_u32 s20, s16, 0x30000
	s_addc_u32 s21, s17, 0
	v_mul_f32_e32 v102, v102, v251
	v_mul_f32_e32 v103, v103, v251
	v_mul_f32_e32 v104, v104, v251
	v_mul_f32_e32 v105, v105, v251
	v_pk_mul_f32 v[102:103], v[102:103], v[142:143]
	v_pk_mul_f32 v[104:105], v[104:105], v[144:145]
	v_mul_f32_e32 v98, v98, v251
	v_mul_f32_e32 v99, v99, v251
	v_mul_f32_e32 v100, v100, v251
	v_mul_f32_e32 v101, v101, v251
	v_pk_mul_f32 v[98:99], v[98:99], v[148:149]
	v_pk_mul_f32 v[100:101], v[100:101], v[150:151]
	v_mul_f32_e32 v38, v38, v251
	v_mul_f32_e32 v39, v39, v251
	v_mul_f32_e32 v40, v40, v251
	v_mul_f32_e32 v41, v41, v251
	v_pk_mul_f32 v[38:39], v[38:39], v[152:153]
	v_pk_mul_f32 v[40:41], v[40:41], v[154:155]
	v_mul_f32_e32 v34, v34, v251
	v_mul_f32_e32 v35, v35, v251
	v_mul_f32_e32 v36, v36, v251
; DEV void final_norm_phase(float* xo, const float* g, int gw, int NGW, int lane) {
;     ...
;         for (int r = 0; r < 2; ++r) {
;             float s = 0.f;
; #pragma unroll
;             for (int j = 0; j < 4; ++j) s += (v[r][j].x * v[r][j].x + v[r][j].y * v[r][j].y) + (v[r][j].z * v[r][j].z + v[r][j].w * v[r][j].w);
;             const float rstd = rsqrtf(wave_sum(s) * (1.f / D) + EPS);
; #pragma unroll
;             for (int j = 0; j < 4; ++j) __builtin_nontemporal_store((v[r][j] * rstd) * gm[j], &xr[r * 256 + 64 * j]);
;         }
	v_mul_f32_e32 v37, v37, v251
	v_pk_mul_f32 v[34:35], v[34:35], v[162:163]
	v_pk_mul_f32 v[36:37], v[36:37], v[164:165]
	global_store_dwordx4 v243, v[102:105], s[20:21] offset:0 nt
	global_store_dwordx4 v243, v[98:101], s[20:21] offset:64 nt
	global_store_dwordx4 v243, v[38:41], s[20:21] offset:512 nt
	global_store_dwordx4 v243, v[34:37], s[20:21] offset:576 nt
	s_add_u32 s20, s16, 0x80000
	s_addc_u32 s21, s17, 0
	v_mul_f32_e32 v94, v94, v244
	v_mul_f32_e32 v95, v95, v244
	v_mul_f32_e32 v96, v96, v244
	v_mul_f32_e32 v97, v97, v244
	v_pk_mul_f32 v[94:95], v[94:95], v[142:143]
	v_pk_mul_f32 v[96:97], v[96:97], v[144:145]
	v_mul_f32_e32 v90, v90, v244
	v_mul_f32_e32 v91, v91, v244
	v_mul_f32_e32 v92, v92, v244
	v_mul_f32_e32 v93, v93, v244
	v_pk_mul_f32 v[90:91], v[90:91], v[148:149]
	v_pk_mul_f32 v[92:93], v[92:93], v[150:151]
	v_mul_f32_e32 v30, v30, v244
	v_mul_f32_e32 v31, v31, v244
	v_mul_f32_e32 v32, v32, v244
	v_mul_f32_e32 v33, v33, v244
	v_pk_mul_f32 v[30:31], v[30:31], v[152:153]
	v_pk_mul_f32 v[32:33], v[32:33], v[154:155]
	v_mul_f32_e32 v26, v26, v244
	v_mul_f32_e32 v27, v27, v244
	v_mul_f32_e32 v28, v28, v244
	v_mul_f32_e32 v29, v29, v244
	v_pk_mul_f32 v[26:27], v[26:27], v[162:163]
	v_pk_mul_f32 v[28:29], v[28:29], v[164:165]
	global_store_dwordx4 v243, v[94:97], s[20:21] offset:0 nt
	global_store_dwordx4 v243, v[90:93], s[20:21] offset:64 nt
	global_store_dwordx4 v243, v[30:33], s[20:21] offset:512 nt
	global_store_dwordx4 v243, v[26:29], s[20:21] offset:576 nt
	s_add_u32 s20, s16, 0x90000
	s_addc_u32 s21, s17, 0
	v_mul_f32_e32 v86, v86, v245
	v_mul_f32_e32 v87, v87, v245
	v_mul_f32_e32 v88, v88, v245
	v_mul_f32_e32 v89, v89, v245
	v_pk_mul_f32 v[86:87], v[86:87], v[142:143]
	v_pk_mul_f32 v[88:89], v[88:89], v[144:145]
	v_mul_f32_e32 v82, v82, v245
	v_mul_f32_e32 v83, v83, v245
	v_mul_f32_e32 v84, v84, v245
	v_mul_f32_e32 v85, v85, v245
	v_pk_mul_f32 v[82:83], v[82:83], v[148:149]
	v_pk_mul_f32 v[84:85], v[84:85], v[150:151]
	v_mul_f32_e32 v22, v22, v245
	v_mul_f32_e32 v23, v23, v245
	v_mul_f32_e32 v24, v24, v245
	v_mul_f32_e32 v25, v25, v245
	v_pk_mul_f32 v[22:23], v[22:23], v[152:153]
	v_pk_mul_f32 v[24:25], v[24:25], v[154:155]
	v_mul_f32_e32 v18, v18, v245
	v_mul_f32_e32 v19, v19, v245
	v_mul_f32_e32 v20, v20, v245
	v_mul_f32_e32 v21, v21, v245
	v_pk_mul_f32 v[18:19], v[18:19], v[162:163]
	v_pk_mul_f32 v[20:21], v[20:21], v[164:165]
	global_store_dwordx4 v243, v[86:89], s[20:21] offset:0 nt
	global_store_dwordx4 v243, v[82:85], s[20:21] offset:64 nt
	global_store_dwordx4 v243, v[22:25], s[20:21] offset:512 nt
	global_store_dwordx4 v243, v[18:21], s[20:21] offset:576 nt
	s_add_u32 s20, s16, 0xa0000
	s_addc_u32 s21, s17, 0
	v_mul_f32_e32 v78, v78, v246
	v_mul_f32_e32 v79, v79, v246
	v_mul_f32_e32 v80, v80, v246
	v_mul_f32_e32 v81, v81, v246
	v_pk_mul_f32 v[78:79], v[78:79], v[142:143]
	v_pk_mul_f32 v[80:81], v[80:81], v[144:145]
	v_mul_f32_e32 v74, v74, v246
	v_mul_f32_e32 v75, v75, v246
	v_mul_f32_e32 v76, v76, v246
	v_mul_f32_e32 v77, v77, v246
	v_pk_mul_f32 v[74:75], v[74:75], v[148:149]
	v_pk_mul_f32 v[76:77], v[76:77], v[150:151]
	v_mul_f32_e32 v14, v14, v246
	v_mul_f32_e32 v15, v15, v246
	v_mul_f32_e32 v16, v16, v246
	v_mul_f32_e32 v17, v17, v246
	v_pk_mul_f32 v[14:15], v[14:15], v[152:153]
	v_pk_mul_f32 v[16:17], v[16:17], v[154:155]
	v_mul_f32_e32 v10, v10, v246
	v_mul_f32_e32 v11, v11, v246
	v_mul_f32_e32 v12, v12, v246
	v_mul_f32_e32 v13, v13, v246
	v_pk_mul_f32 v[10:11], v[10:11], v[162:163]
	v_pk_mul_f32 v[12:13], v[12:13], v[164:165]
	global_store_dwordx4 v243, v[78:81], s[20:21] offset:0 nt
	global_store_dwordx4 v243, v[74:77], s[20:21] offset:64 nt
	global_store_dwordx4 v243, v[14:17], s[20:21] offset:512 nt
	global_store_dwordx4 v243, v[10:13], s[20:21] offset:576 nt
	s_add_u32 s20, s16, 0xb0000
	s_addc_u32 s21, s17, 0
	v_mul_f32_e32 v62, v62, v247
	v_mul_f32_e32 v63, v63, v247
	v_mul_f32_e32 v64, v64, v247
	v_mul_f32_e32 v65, v65, v247
	v_pk_mul_f32 v[62:63], v[62:63], v[142:143]
	v_pk_mul_f32 v[64:65], v[64:65], v[144:145]
	v_mul_f32_e32 v58, v58, v247
	v_mul_f32_e32 v59, v59, v247
	v_mul_f32_e32 v60, v60, v247
	v_mul_f32_e32 v61, v61, v247
	v_pk_mul_f32 v[58:59], v[58:59], v[148:149]
	v_pk_mul_f32 v[60:61], v[60:61], v[150:151]
	v_mul_f32_e32 v6, v6, v247
	v_mul_f32_e32 v7, v7, v247
	v_mul_f32_e32 v8, v8, v247
	v_mul_f32_e32 v9, v9, v247
	v_pk_mul_f32 v[6:7], v[6:7], v[152:153]
	v_pk_mul_f32 v[8:9], v[8:9], v[154:155]
	v_mul_f32_e32 v2, v2, v247
	v_mul_f32_e32 v3, v3, v247
	v_mul_f32_e32 v4, v4, v247
	v_mul_f32_e32 v5, v5, v247
	v_pk_mul_f32 v[2:3], v[2:3], v[162:163]
	v_pk_mul_f32 v[4:5], v[4:5], v[164:165]
	global_store_dwordx4 v243, v[62:65], s[20:21] offset:0 nt
	global_store_dwordx4 v243, v[58:61], s[20:21] offset:64 nt
	global_store_dwordx4 v243, v[6:9], s[20:21] offset:512 nt
	global_store_dwordx4 v243, v[2:5], s[20:21] offset:576 nt
	s_mov_b64 s[34:35], -1
	s_and_b64 vcc, exec, s[4:5]
	s_cbranch_vccnz .LBB0_1976
	s_andn2_b64 vcc, exec, s[10:11]
	s_cbranch_vccnz .LBB0_1975
	s_barrier
	s_branch .LBB0_1975

; #define SEAM(k) do { if (IN(k) && IN((k) + 1)) { if (a.ph_hi > 4096) cg::this_grid().sync(); else xcd_barrier(xbar); } } while (0)
; __global__ void __launch_bounds__(512, 2) fwd_kernel(Args a) {
;     ...
;     if (IN(13)) { pg8::Gemm g{ZH, (const bf16_t*)(ws + WS_W2B), MLAT, D, DFF}; pg8::StaticOrder S; S.init(MLAT, D, G, (int)blockIdx.x); typedef EpiResid<8, true, false, 0> EpiT; EpiT E{a.out, a.out, a.out, a.out, mod, nullptr, nullptr, nullptr};
;         pg8::gemm_phase<EpiT, pg8::StaticOrder, true, true>(ldsg, g, S, E); } SEAM(13);
;     if (IN(14)) { final_norm_phase(a.out, a.in[I_FING], gw, NGW, lane); }
.LBB0_1997:
.LBB0_2065:
	s_endpgm
